# cand A + prepass_sample pool-state rows prefetched during the conv (pool round trip overlaps conv/LN barrier)
# speedup vs baseline: 1.0166x; 1.0070x over previous
.LBB0_579:
	s_or_b64 exec, exec, s[76:77]
	v_pk_mul_f32 v[8:9], v[8:9], v[12:13]
	v_readlane_b32 s4, v252, 56
	v_pk_fma_f32 v[6:7], v[6:7], v[10:11], v[8:9]
	v_and_b32_e32 v8, 0xffff0000, v40
	v_pk_fma_f32 v[6:7], v[16:17], v[14:15], v[6:7]
	s_waitcnt lgkmcnt(0)
	s_barrier
	v_mul_f32_e32 v12, v7, v8
	v_lshlrev_b32_e32 v7, 16, v40
	v_mul_f32_e32 v13, v6, v7
	v_mov_b32_e32 v6, s4
	v_readlane_b32 s4, v252, 57
	ds_read2_b32 v[6:7], v6 offset1:1
	v_lshlrev_b32_e32 v14, 16, v39
	v_mov_b32_e32 v8, s4
	ds_read2_b32 v[8:9], v8 offset1:1
	v_readlane_b32 s4, v252, 58
	s_waitcnt lgkmcnt(1)
	v_pk_add_f32 v[6:7], v[6:7], 0 op_sel_hi:[1,0]
	s_lshl_b64 s[38:39], s[38:39], 11
	s_add_u32 s42, s73, s38
	s_waitcnt lgkmcnt(0)
	v_pk_add_f32 v[6:7], v[6:7], v[8:9]
	v_mov_b32_e32 v8, s4
	ds_read2_b32 v[8:9], v8 offset1:1
	v_readlane_b32 s4, v252, 59
	s_addc_u32 s43, s82, s39
	v_lshlrev_b64 v[4:5], 1, v[4:5]
	v_mov_b32_e32 v16, 0xf000
	s_waitcnt lgkmcnt(0)
	v_pk_add_f32 v[6:7], v[6:7], v[8:9]
	v_mov_b32_e32 v8, s4
	ds_read2_b32 v[8:9], v8 offset1:1
	v_readlane_b32 s4, v253, 51
	s_waitcnt lgkmcnt(0)
	v_pk_add_f32 v[6:7], v[6:7], v[8:9]
	v_mov_b32_e32 v8, s4
	ds_read2_b32 v[8:9], v8 offset1:1
	v_readlane_b32 s4, v253, 53
	s_waitcnt lgkmcnt(0)
	v_pk_add_f32 v[6:7], v[6:7], v[8:9]
	v_mov_b32_e32 v8, s4
	ds_read2_b32 v[8:9], v8 offset1:1
	v_readlane_b32 s4, v253, 55
	s_waitcnt lgkmcnt(0)
	v_pk_add_f32 v[6:7], v[6:7], v[8:9]
	v_mov_b32_e32 v8, s4
	ds_read2_b32 v[8:9], v8 offset1:1
	v_readlane_b32 s4, v253, 57
	s_waitcnt lgkmcnt(0)
	v_pk_add_f32 v[6:7], v[6:7], v[8:9]
	v_mov_b32_e32 v8, s4
	ds_read2_b32 v[8:9], v8 offset1:1
	v_readlane_b32 s4, v253, 59
	v_readlane_b32 s5, v253, 60
	s_waitcnt lgkmcnt(0)
	v_pk_add_f32 v[6:7], v[6:7], v[8:9]
	s_nop 0
	v_pk_mul_f32 v[6:7], v[6:7], s[84:85] op_sel_hi:[1,0]
	s_nop 0
	v_fma_f32 v8, -v6, v6, v7
	v_add_f32_e32 v8, 0x358637bd, v8
	v_cmp_gt_f32_e32 vcc, s33, v8
	v_mul_f32_e32 v9, 0x4b800000, v8
	v_pk_add_f32 v[6:7], v[32:33], v[6:7] op_sel_hi:[1,0] neg_lo:[0,1] neg_hi:[0,1]
	v_cndmask_b32_e32 v8, v8, v9, vcc
	v_rsq_f32_e32 v8, v8
	s_nop 0
	v_mul_f32_e32 v9, 0x45800000, v8
	v_cndmask_b32_e32 v8, v8, v9, vcc
	v_pk_mul_f32 v[6:7], v[6:7], v[8:9] op_sel_hi:[1,0]
	v_lshl_add_u64 v[8:9], s[4:5], 0, v[2:3]
	v_readlane_b32 s4, v253, 61
	v_readlane_b32 s5, v253, 62
	global_load_dwordx2 v[8:9], v[8:9], off
	s_nop 0
	v_lshl_add_u64 v[10:11], s[4:5], 0, v[2:3]
	global_load_dwordx2 v[10:11], v[10:11], off
	v_readlane_b32 s4, v253, 63
	v_readlane_b32 s5, v255, 0
	s_waitcnt vmcnt(0)
	v_pk_fma_f32 v[6:7], v[8:9], v[6:7], v[10:11]
	s_nop 0
	v_mul_f32_e32 v8, 0xbfb8aa3b, v6
	v_exp_f32_e32 v8, v8
	s_nop 0
	v_add_f32_e32 v8, 1.0, v8
	v_rcp_f32_e32 v8, v8
	s_nop 0
	v_mul_f32_e32 v10, v6, v8
	v_mul_f32_e32 v6, 0xbfb8aa3b, v7
	v_exp_f32_e32 v6, v6
	s_nop 0
	v_add_f32_e32 v6, 1.0, v6
	v_rcp_f32_e32 v6, v6
	s_nop 0
	v_mul_f32_e32 v11, v7, v6
	v_lshl_add_u64 v[6:7], s[4:5], 0, v[2:3]
	v_readlane_b32 s4, v255, 1
	v_readlane_b32 s5, v255, 2
	global_load_dwordx2 v[6:7], v[6:7], off
	s_nop 0
	v_lshl_add_u64 v[8:9], s[4:5], 0, v[2:3]
	global_load_dwordx2 v[8:9], v[8:9], off
	v_readlane_b32 s4, v253, 0
	v_readlane_b32 s5, v253, 1
	s_waitcnt vmcnt(1)
	v_add_f32_e32 v6, v6, v14
	v_lshlrev_b32_e32 v14, 16, v38
	v_mul_f32_e32 v6, 0xbfb8aa3b, v6
	s_waitcnt vmcnt(0)
	v_add_f32_e32 v8, v8, v14
	v_mul_f32_e32 v8, 0xbfb8aa3b, v8
	v_exp_f32_e32 v8, v8
	v_exp_f32_e32 v6, v6
	v_add_f32_e32 v8, 1.0, v8
	v_add_f32_e32 v6, 1.0, v6
	v_rcp_f32_e32 v8, v8
	v_rcp_f32_e32 v6, v6
	v_mul_f32_e32 v8, v8, v10
	v_fmac_f32_e32 v8, v13, v6
	v_and_b32_e32 v6, 0xffff0000, v39
	v_add_f32_e32 v6, v7, v6
	v_and_b32_e32 v7, 0xffff0000, v38
	v_add_f32_e32 v7, v9, v7
	v_mul_f32_e32 v7, 0xbfb8aa3b, v7
	v_mul_f32_e32 v6, 0xbfb8aa3b, v6
	v_exp_f32_e32 v7, v7
	v_exp_f32_e32 v6, v6
	v_add_f32_e32 v7, 1.0, v7
	v_add_f32_e32 v6, 1.0, v6
	v_rcp_f32_e32 v7, v7
	v_rcp_f32_e32 v6, v6
	v_mul_f32_e32 v7, v7, v11
	v_fmac_f32_e32 v7, v12, v6
	v_cvt_pk_bf16_f32 v8, v8, v7
	v_lshl_add_u64 v[6:7], s[42:43], 0, v[4:5]
	v_lshl_add_u64 v[10:11], s[4:5], 0, v[2:3]
	s_mul_i32 s43, s37, 0xf000
	s_mul_hi_u32 s37, s36, 0xf000
	v_readlane_b32 s4, v252, 2
	s_add_i32 s37, s37, s43
	s_mul_i32 s42, s36, 0xf000
	v_readlane_b32 s18, v252, 16
	v_readlane_b32 s19, v252, 17
	s_add_u32 s44, s18, s42
	v_readlane_b32 s5, v252, 3
	s_addc_u32 s45, s19, s37
	global_store_dword v[6:7], v8, off
	v_lshl_add_u64 v[8:9], s[44:45], 0, v[2:3]
	s_movk_i32 s5, 0x2000
	v_mad_u64_u32 v[10:11], s[44:45], s36, v16, v[10:11]
	v_add_u32_e32 v11, s43, v11
	s_mov_b32 s45, 0
	s_waitcnt vmcnt(0)
	v_mov_b64_e32 v[6:7], v[44:45]
	v_mov_b64_e32 v[14:15], v[46:47]
	v_mov_b64_e32 v[12:13], v[48:49]
	v_mov_b64_e32 v[18:19], v[50:51]
	v_mov_b64_e32 v[16:17], v[52:53]
	v_mov_b64_e32 v[22:23], v[54:55]
	v_mov_b64_e32 v[20:21], v[56:57]
	v_mov_b64_e32 v[26:27], v[58:59]
	v_mov_b64_e32 v[24:25], v[60:61]
	v_mov_b64_e32 v[30:31], v[62:63]
	v_mov_b64_e32 v[28:29], v[64:65]
	v_mov_b64_e32 v[34:35], v[66:67]
	v_mov_b64_e32 v[32:33], v[68:69]
	v_mov_b64_e32 v[36:37], v[70:71]
	v_mov_b64_e32 v[38:39], v[72:73]
	v_readlane_b32 s6, v252, 4
	s_movk_i32 s6, 0x4000
	s_movk_i32 s4, 0x6000
	v_readlane_b32 s8, v252, 6
	v_readlane_b32 s9, v252, 7
	v_readlane_b32 s8, v255, 13
	v_readlane_b32 s9, v255, 14
	v_readlane_b32 s7, v252, 5
	s_mul_i32 s7, s96, 0x1e000
	v_readlane_b32 s14, v252, 12
	v_readlane_b32 s15, v252, 13
	v_readlane_b32 s10, v252, 8
	v_readlane_b32 s11, v252, 9
	v_readlane_b32 s12, v252, 10
	v_readlane_b32 s13, v252, 11
	v_readlane_b32 s16, v252, 14
	v_readlane_b32 s17, v252, 15
	v_readlane_b32 s4, v253, 2
	s_add_u32 s36, s4, s42
	v_readlane_b32 s4, v253, 3
	s_addc_u32 s37, s4, s37
	v_lshl_add_u64 v[2:3], s[36:37], 0, v[2:3]
	s_add_u32 s36, s85, s38
	s_addc_u32 s37, s88, s39
	s_add_i32 s50, s50, s96
	s_add_u32 s34, s34, s7
	s_mul_hi_i32 s4, s96, 0x1e000
	s_addc_u32 s35, s35, s4
	s_add_u32 s0, s0, s7
	s_addc_u32 s1, s1, s4
	s_cmpk_gt_i32 s50, 0x7f
	s_mov_b32 s44, 0x2000
	v_lshl_add_u64 v[42:43], v[10:11], 0, s[44:45]
	global_store_dwordx2 v[42:43], v[14:15], off offset:-4096
	global_store_dwordx2 v[42:43], v[12:13], off
	s_mov_b32 s44, 0x4000
	v_lshl_add_u64 v[42:43], v[10:11], 0, s[44:45]
	global_store_dwordx2 v[42:43], v[18:19], off offset:-4096
	global_store_dwordx2 v[42:43], v[16:17], off
	s_mov_b32 s44, 0x6000
	v_lshl_add_u64 v[42:43], v[10:11], 0, s[44:45]
	global_store_dwordx2 v[42:43], v[22:23], off offset:-4096
	global_store_dwordx2 v[42:43], v[20:21], off
	s_mov_b32 s44, 0x8000
	v_lshl_add_u64 v[42:43], v[10:11], 0, s[44:45]
	global_store_dwordx2 v[42:43], v[26:27], off offset:-4096
	global_store_dwordx2 v[42:43], v[24:25], off
	s_mov_b32 s44, 0xa000
	v_lshl_add_u64 v[42:43], v[10:11], 0, s[44:45]
	global_store_dwordx2 v[42:43], v[30:31], off offset:-4096
	global_store_dwordx2 v[42:43], v[28:29], off
	s_mov_b32 s44, 0xc000
	v_lshl_add_u64 v[42:43], v[10:11], 0, s[44:45]
	global_store_dwordx2 v[42:43], v[34:35], off offset:-4096
	global_store_dwordx2 v[42:43], v[32:33], off
	s_mov_b32 s44, 0xe000
	v_lshl_add_u64 v[42:43], v[10:11], 0, s[44:45]
	global_store_dwordx2 v[42:43], v[36:37], off offset:-4096
	global_store_dwordx2 v[42:43], v[38:39], off
	v_lshlrev_b32_e32 v8, 16, v0
	v_and_b32_e32 v9, 0xffff0000, v0
	v_pk_add_f32 v[6:7], v[6:7], v[8:9]
	global_store_dwordx2 v[2:3], v[8:9], off
	v_cndmask_b32_e64 v7, v7, v9, s[30:31]
	v_cndmask_b32_e64 v6, v6, v8, s[30:31]
	v_pk_add_f32 v[6:7], v[14:15], v[6:7]
	v_cndmask_b32_e64 v7, v7, v9, s[28:29]
	v_cndmask_b32_e64 v6, v6, v8, s[28:29]
	v_pk_add_f32 v[6:7], v[12:13], v[6:7]
	s_nop 0
	v_cndmask_b32_e64 v7, v7, v9, s[26:27]
	v_cndmask_b32_e64 v6, v6, v8, s[26:27]
	v_pk_add_f32 v[6:7], v[18:19], v[6:7]
	s_nop 0
	v_cndmask_b32_e64 v7, v7, v9, s[24:25]
	v_cndmask_b32_e64 v6, v6, v8, s[24:25]
	v_pk_add_f32 v[6:7], v[16:17], v[6:7]
	s_nop 0
	v_cndmask_b32_e64 v7, v7, v9, s[22:23]
	v_cndmask_b32_e64 v6, v6, v8, s[22:23]
	v_pk_add_f32 v[6:7], v[22:23], v[6:7]
	s_nop 0
	v_cndmask_b32_e64 v7, v7, v9, s[20:21]
	v_cndmask_b32_e64 v6, v6, v8, s[20:21]
	v_pk_add_f32 v[6:7], v[20:21], v[6:7]
	s_nop 0
	v_cndmask_b32_e64 v7, v7, v9, s[8:9]
	v_cndmask_b32_e64 v6, v6, v8, s[8:9]
	v_readlane_b32 s8, v255, 11
	v_pk_add_f32 v[6:7], v[26:27], v[6:7]
	v_readlane_b32 s9, v255, 12
	s_nop 1
	v_cndmask_b32_e64 v7, v7, v9, s[8:9]
	v_cndmask_b32_e64 v6, v6, v8, s[8:9]
	v_readlane_b32 s8, v255, 9
	v_pk_add_f32 v[6:7], v[24:25], v[6:7]
	v_readlane_b32 s9, v255, 10
	s_nop 1
	v_cndmask_b32_e64 v7, v7, v9, s[8:9]
	v_cndmask_b32_e64 v6, v6, v8, s[8:9]
	v_readlane_b32 s8, v255, 7
	v_pk_add_f32 v[6:7], v[30:31], v[6:7]
	v_readlane_b32 s9, v255, 8
	s_nop 1
	v_cndmask_b32_e64 v7, v7, v9, s[8:9]
	v_cndmask_b32_e64 v6, v6, v8, s[8:9]
	v_pk_add_f32 v[6:7], v[28:29], v[6:7]
	v_readlane_b32 s8, v255, 5
	v_cndmask_b32_e64 v7, v7, v9, s[2:3]
	v_cndmask_b32_e64 v6, v6, v8, s[2:3]
	v_pk_add_f32 v[6:7], v[34:35], v[6:7]
	v_readlane_b32 s9, v255, 6
	v_cndmask_b32_e64 v7, v7, v9, s[78:79]
	v_cndmask_b32_e64 v6, v6, v8, s[78:79]
	v_pk_add_f32 v[6:7], v[32:33], v[6:7]
	s_nop 0
	v_cndmask_b32_e64 v7, v7, v9, s[46:47]
	v_cndmask_b32_e64 v6, v6, v8, s[46:47]
	v_pk_add_f32 v[6:7], v[36:37], v[6:7]
	s_nop 0
	v_cndmask_b32_e64 v7, v7, v9, s[8:9]
	v_cndmask_b32_e64 v6, v6, v8, s[8:9]
	v_readlane_b32 s8, v255, 3
	v_pk_add_f32 v[6:7], v[38:39], v[6:7]
	v_readlane_b32 s9, v255, 4
	s_nop 1
	v_cndmask_b32_e64 v0, v7, v9, s[8:9]
	v_cndmask_b32_e64 v6, v6, v8, s[8:9]
	v_fma_f32 v2, v161, v6, -v8
	v_fma_f32 v0, v161, v0, -v9
	v_cvt_pk_bf16_f32 v0, v2, v0
	v_lshl_add_u64 v[2:3], s[36:37], 0, v[4:5]
	global_store_dword v[2:3], v0, off
	s_waitcnt lgkmcnt(0)
	s_barrier
	s_cbranch_scc1 .LBB0_570

.LBB0_582:
	s_mov_b32 s45, 0
	s_mov_b32 s44, 0x1000
	v_lshl_add_u64 v[42:43], v[24:25], 0, s[44:45]
	global_load_dwordx2 v[44:45], v[42:43], off offset:-4096
	global_load_dwordx2 v[46:47], v[42:43], off
	v_lshl_add_u64 v[42:43], v[20:21], 0, s[44:45]
	global_load_dwordx2 v[104:105], v[42:43], off offset:-4096
	global_load_dwordx2 v[106:107], v[42:43], off
	s_mov_b32 s44, 0x3000
	v_lshl_add_u64 v[42:43], v[24:25], 0, s[44:45]
	global_load_dwordx2 v[48:49], v[42:43], off offset:-4096
	global_load_dwordx2 v[50:51], v[42:43], off
	v_lshl_add_u64 v[42:43], v[20:21], 0, s[44:45]
	global_load_dwordx2 v[108:109], v[42:43], off offset:-4096
	global_load_dwordx2 v[110:111], v[42:43], off
	s_mov_b32 s44, 0x5000
	v_lshl_add_u64 v[42:43], v[24:25], 0, s[44:45]
	global_load_dwordx2 v[52:53], v[42:43], off offset:-4096
	global_load_dwordx2 v[54:55], v[42:43], off
	v_lshl_add_u64 v[42:43], v[20:21], 0, s[44:45]
	global_load_dwordx2 v[112:113], v[42:43], off offset:-4096
	global_load_dwordx2 v[114:115], v[42:43], off
	s_mov_b32 s44, 0x7000
	v_lshl_add_u64 v[42:43], v[24:25], 0, s[44:45]
	global_load_dwordx2 v[56:57], v[42:43], off offset:-4096
	global_load_dwordx2 v[58:59], v[42:43], off
	v_lshl_add_u64 v[42:43], v[20:21], 0, s[44:45]
	global_load_dwordx2 v[116:117], v[42:43], off offset:-4096
	global_load_dwordx2 v[118:119], v[42:43], off
	s_mov_b32 s44, 0x9000
	v_lshl_add_u64 v[42:43], v[24:25], 0, s[44:45]
	global_load_dwordx2 v[60:61], v[42:43], off offset:-4096
	global_load_dwordx2 v[62:63], v[42:43], off
	v_lshl_add_u64 v[42:43], v[20:21], 0, s[44:45]
	global_load_dwordx2 v[120:121], v[42:43], off offset:-4096
	global_load_dwordx2 v[122:123], v[42:43], off
	s_mov_b32 s44, 0xb000
	v_lshl_add_u64 v[42:43], v[24:25], 0, s[44:45]
	global_load_dwordx2 v[64:65], v[42:43], off offset:-4096
	global_load_dwordx2 v[66:67], v[42:43], off
	v_lshl_add_u64 v[42:43], v[20:21], 0, s[44:45]
	global_load_dwordx2 v[124:125], v[42:43], off offset:-4096
	global_load_dwordx2 v[126:127], v[42:43], off
	s_mov_b32 s44, 0xd000
	v_lshl_add_u64 v[42:43], v[24:25], 0, s[44:45]
	global_load_dwordx2 v[68:69], v[42:43], off offset:-4096
	global_load_dwordx2 v[70:71], v[42:43], off
	v_lshl_add_u64 v[42:43], v[20:21], 0, s[44:45]
	global_load_dwordx2 v[128:129], v[42:43], off offset:-4096
	global_load_dwordx2 v[130:131], v[42:43], off
	s_mov_b32 s44, 0xf000
	v_lshl_add_u64 v[42:43], v[24:25], 0, s[44:45]
	global_load_dwordx2 v[72:73], v[42:43], off offset:-4096
	global_load_dwordx2 v[74:75], v[42:43], off
	v_lshl_add_u64 v[42:43], v[20:21], 0, s[44:45]
	global_load_dwordx2 v[132:133], v[42:43], off offset:-4096
	global_load_dwordx2 v[134:135], v[42:43], off
	s_mov_b32 s44, 0x11000
	v_lshl_add_u64 v[42:43], v[24:25], 0, s[44:45]
	global_load_dwordx2 v[76:77], v[42:43], off offset:-4096
	global_load_dwordx2 v[78:79], v[42:43], off
	v_lshl_add_u64 v[42:43], v[20:21], 0, s[44:45]
	global_load_dwordx2 v[136:137], v[42:43], off offset:-4096
	global_load_dwordx2 v[138:139], v[42:43], off
	s_mov_b32 s44, 0x13000
	v_lshl_add_u64 v[42:43], v[24:25], 0, s[44:45]
	global_load_dwordx2 v[80:81], v[42:43], off offset:-4096
	global_load_dwordx2 v[82:83], v[42:43], off
	v_lshl_add_u64 v[42:43], v[20:21], 0, s[44:45]
	global_load_dwordx2 v[140:141], v[42:43], off offset:-4096
	global_load_dwordx2 v[142:143], v[42:43], off
	s_mov_b32 s44, 0x15000
	v_lshl_add_u64 v[42:43], v[24:25], 0, s[44:45]
	global_load_dwordx2 v[84:85], v[42:43], off offset:-4096
	global_load_dwordx2 v[86:87], v[42:43], off
	v_lshl_add_u64 v[42:43], v[20:21], 0, s[44:45]
	global_load_dwordx2 v[144:145], v[42:43], off offset:-4096
	global_load_dwordx2 v[146:147], v[42:43], off
	s_mov_b32 s44, 0x17000
	v_lshl_add_u64 v[42:43], v[24:25], 0, s[44:45]
	global_load_dwordx2 v[88:89], v[42:43], off offset:-4096
	global_load_dwordx2 v[90:91], v[42:43], off
	v_lshl_add_u64 v[42:43], v[20:21], 0, s[44:45]
	global_load_dwordx2 v[148:149], v[42:43], off offset:-4096
	global_load_dwordx2 v[150:151], v[42:43], off
	s_mov_b32 s44, 0x19000
	v_lshl_add_u64 v[42:43], v[24:25], 0, s[44:45]
	global_load_dwordx2 v[92:93], v[42:43], off offset:-4096
	global_load_dwordx2 v[94:95], v[42:43], off
	v_lshl_add_u64 v[42:43], v[20:21], 0, s[44:45]
	global_load_dwordx2 v[152:153], v[42:43], off offset:-4096
	global_load_dwordx2 v[154:155], v[42:43], off
	s_mov_b32 s44, 0x1b000
	v_lshl_add_u64 v[42:43], v[24:25], 0, s[44:45]
	global_load_dwordx2 v[96:97], v[42:43], off offset:-4096
	global_load_dwordx2 v[98:99], v[42:43], off
	v_lshl_add_u64 v[42:43], v[20:21], 0, s[44:45]
	global_load_dwordx2 v[156:157], v[42:43], off offset:-4096
	global_load_dwordx2 v[158:159], v[42:43], off
	s_mov_b32 s44, 0x1d000
	v_lshl_add_u64 v[42:43], v[24:25], 0, s[44:45]
	global_load_dwordx2 v[100:101], v[42:43], off offset:-4096
	global_load_dwordx2 v[102:103], v[42:43], off
	v_lshl_add_u64 v[42:43], v[20:21], 0, s[44:45]
	global_load_dwordx2 v[34:35], v[42:43], off offset:-4096
	global_load_dwordx2 v[36:37], v[42:43], off
	s_waitcnt vmcnt(57)
	v_pk_fma_f32 v[32:33], v[44:45], v[104:105], v[32:33]
	s_waitcnt vmcnt(56)
	v_pk_fma_f32 v[32:33], v[46:47], v[106:107], v[32:33]
	s_mov_b32 s44, 0x6570000
	v_lshl_add_u64 v[42:43], v[22:23], 0, s[44:45]
	global_store_dwordx2 v[42:43], v[46:47], off
	s_waitcnt vmcnt(54)
	v_pk_fma_f32 v[32:33], v[48:49], v[108:109], v[32:33]
	s_mov_b32 s44, 0x6571000
	v_lshl_add_u64 v[42:43], v[22:23], 0, s[44:45]
	global_store_dwordx2 v[42:43], v[48:49], off
	s_waitcnt vmcnt(54)
	v_pk_fma_f32 v[32:33], v[50:51], v[110:111], v[32:33]
	s_mov_b32 s44, 0x6572000
	v_lshl_add_u64 v[42:43], v[22:23], 0, s[44:45]
	global_store_dwordx2 v[42:43], v[50:51], off
	s_waitcnt vmcnt(52)
	v_pk_fma_f32 v[32:33], v[52:53], v[112:113], v[32:33]
	s_mov_b32 s44, 0x6573000
	v_lshl_add_u64 v[42:43], v[22:23], 0, s[44:45]
	global_store_dwordx2 v[42:43], v[52:53], off
	s_waitcnt vmcnt(52)
	v_pk_fma_f32 v[32:33], v[54:55], v[114:115], v[32:33]
	s_mov_b32 s44, 0x6574000
	v_lshl_add_u64 v[42:43], v[22:23], 0, s[44:45]
	global_store_dwordx2 v[42:43], v[54:55], off
	s_waitcnt vmcnt(50)
	v_pk_fma_f32 v[32:33], v[56:57], v[116:117], v[32:33]
	s_mov_b32 s44, 0x6575000
	v_lshl_add_u64 v[42:43], v[22:23], 0, s[44:45]
	global_store_dwordx2 v[42:43], v[56:57], off
	s_waitcnt vmcnt(50)
	v_pk_fma_f32 v[32:33], v[58:59], v[118:119], v[32:33]
	s_mov_b32 s44, 0x6576000
	v_lshl_add_u64 v[42:43], v[22:23], 0, s[44:45]
	global_store_dwordx2 v[42:43], v[58:59], off
	s_waitcnt vmcnt(48)
	v_pk_fma_f32 v[32:33], v[60:61], v[120:121], v[32:33]
	s_mov_b32 s44, 0x6577000
	v_lshl_add_u64 v[42:43], v[22:23], 0, s[44:45]
	global_store_dwordx2 v[42:43], v[60:61], off
	s_waitcnt vmcnt(48)
	v_pk_fma_f32 v[32:33], v[62:63], v[122:123], v[32:33]
	s_mov_b32 s44, 0x6578000
	v_lshl_add_u64 v[42:43], v[22:23], 0, s[44:45]
	global_store_dwordx2 v[42:43], v[62:63], off
	s_waitcnt vmcnt(46)
	v_pk_fma_f32 v[32:33], v[64:65], v[124:125], v[32:33]
	s_mov_b32 s44, 0x6579000
	v_lshl_add_u64 v[42:43], v[22:23], 0, s[44:45]
	global_store_dwordx2 v[42:43], v[64:65], off
	s_waitcnt vmcnt(46)
	v_pk_fma_f32 v[32:33], v[66:67], v[126:127], v[32:33]
	s_mov_b32 s44, 0x657a000
	v_lshl_add_u64 v[42:43], v[22:23], 0, s[44:45]
	global_store_dwordx2 v[42:43], v[66:67], off
	s_waitcnt vmcnt(44)
	v_pk_fma_f32 v[32:33], v[68:69], v[128:129], v[32:33]
	s_mov_b32 s44, 0x657b000
	v_lshl_add_u64 v[42:43], v[22:23], 0, s[44:45]
	global_store_dwordx2 v[42:43], v[68:69], off
	s_waitcnt vmcnt(44)
	v_pk_fma_f32 v[32:33], v[70:71], v[130:131], v[32:33]
	s_mov_b32 s44, 0x657c000
	v_lshl_add_u64 v[42:43], v[22:23], 0, s[44:45]
	global_store_dwordx2 v[42:43], v[70:71], off
	s_waitcnt vmcnt(42)
	v_pk_fma_f32 v[32:33], v[72:73], v[132:133], v[32:33]
	s_mov_b32 s44, 0x657d000
	v_lshl_add_u64 v[42:43], v[22:23], 0, s[44:45]
	global_store_dwordx2 v[42:43], v[72:73], off
	s_mul_i32 s98, s37, 0xf000
	s_mul_hi_u32 s99, s36, 0xf000
	s_add_i32 s99, s99, s98
	s_mul_i32 s98, s36, 0xf000
	v_readlane_b32 s100, v252, 16
	v_readlane_b32 s101, v252, 17
	s_nop 3
	s_add_u32 s98, s100, s98
	s_addc_u32 s99, s101, s99
	v_lshl_add_u64 v[104:105], s[98:99], 0, v[2:3]
	global_load_dwordx2 v[44:45], v[104:105], off
	s_mov_b32 s44, 0x2000
	v_lshl_add_u64 v[106:107], v[104:105], 0, s[44:45]
	global_load_dwordx2 v[46:47], v[106:107], off offset:-4096
	global_load_dwordx2 v[48:49], v[106:107], off
	s_mov_b32 s44, 0x4000
	v_lshl_add_u64 v[106:107], v[104:105], 0, s[44:45]
	global_load_dwordx2 v[50:51], v[106:107], off offset:-4096
	global_load_dwordx2 v[52:53], v[106:107], off
	s_mov_b32 s44, 0x6000
	v_lshl_add_u64 v[106:107], v[104:105], 0, s[44:45]
	global_load_dwordx2 v[54:55], v[106:107], off offset:-4096
	global_load_dwordx2 v[56:57], v[106:107], off
	s_mov_b32 s44, 0x8000
	v_lshl_add_u64 v[106:107], v[104:105], 0, s[44:45]
	global_load_dwordx2 v[58:59], v[106:107], off offset:-4096
	global_load_dwordx2 v[60:61], v[106:107], off
	s_mov_b32 s44, 0xa000
	v_lshl_add_u64 v[106:107], v[104:105], 0, s[44:45]
	global_load_dwordx2 v[62:63], v[106:107], off offset:-4096
	global_load_dwordx2 v[64:65], v[106:107], off
	s_mov_b32 s44, 0xc000
	v_lshl_add_u64 v[106:107], v[104:105], 0, s[44:45]
	global_load_dwordx2 v[66:67], v[106:107], off offset:-4096
	global_load_dwordx2 v[68:69], v[106:107], off
	s_mov_b32 s44, 0xe000
	v_lshl_add_u64 v[106:107], v[104:105], 0, s[44:45]
	global_load_dwordx2 v[70:71], v[106:107], off offset:-4096
	global_load_dwordx2 v[72:73], v[106:107], off
	s_waitcnt vmcnt(57)
	v_pk_fma_f32 v[32:33], v[74:75], v[134:135], v[32:33]
	s_mov_b32 s44, 0x657e000
	v_lshl_add_u64 v[42:43], v[22:23], 0, s[44:45]
	global_store_dwordx2 v[42:43], v[74:75], off
	s_waitcnt vmcnt(55)
	v_pk_fma_f32 v[32:33], v[76:77], v[136:137], v[32:33]
	s_mov_b32 s44, 0x657f000
	v_lshl_add_u64 v[42:43], v[22:23], 0, s[44:45]
	global_store_dwordx2 v[42:43], v[76:77], off
	s_waitcnt vmcnt(55)
	v_pk_fma_f32 v[32:33], v[78:79], v[138:139], v[32:33]
	s_mov_b32 s44, 0x6580000
	v_lshl_add_u64 v[42:43], v[22:23], 0, s[44:45]
	global_store_dwordx2 v[42:43], v[78:79], off
	s_waitcnt vmcnt(53)
	v_pk_fma_f32 v[32:33], v[80:81], v[140:141], v[32:33]
	s_mov_b32 s44, 0x6581000
	v_lshl_add_u64 v[42:43], v[22:23], 0, s[44:45]
	global_store_dwordx2 v[42:43], v[80:81], off
	s_waitcnt vmcnt(53)
	v_pk_fma_f32 v[32:33], v[82:83], v[142:143], v[32:33]
	s_mov_b32 s44, 0x6582000
	v_lshl_add_u64 v[42:43], v[22:23], 0, s[44:45]
	global_store_dwordx2 v[42:43], v[82:83], off
	s_waitcnt vmcnt(51)
	v_pk_fma_f32 v[32:33], v[84:85], v[144:145], v[32:33]
	s_mov_b32 s44, 0x6583000
	v_lshl_add_u64 v[42:43], v[22:23], 0, s[44:45]
	global_store_dwordx2 v[42:43], v[84:85], off
	s_waitcnt vmcnt(51)
	v_pk_fma_f32 v[32:33], v[86:87], v[146:147], v[32:33]
	s_mov_b32 s44, 0x6584000
	v_lshl_add_u64 v[42:43], v[22:23], 0, s[44:45]
	global_store_dwordx2 v[42:43], v[86:87], off
	s_waitcnt vmcnt(49)
	v_pk_fma_f32 v[32:33], v[88:89], v[148:149], v[32:33]
	s_mov_b32 s44, 0x6585000
	v_lshl_add_u64 v[42:43], v[22:23], 0, s[44:45]
	global_store_dwordx2 v[42:43], v[88:89], off
	s_waitcnt vmcnt(49)
	v_pk_fma_f32 v[32:33], v[90:91], v[150:151], v[32:33]
	s_mov_b32 s44, 0x6586000
	v_lshl_add_u64 v[42:43], v[22:23], 0, s[44:45]
	global_store_dwordx2 v[42:43], v[90:91], off
	s_waitcnt vmcnt(47)
	v_pk_fma_f32 v[32:33], v[92:93], v[152:153], v[32:33]
	s_mov_b32 s44, 0x6587000
	v_lshl_add_u64 v[42:43], v[22:23], 0, s[44:45]
	global_store_dwordx2 v[42:43], v[92:93], off
	s_waitcnt vmcnt(47)
	v_pk_fma_f32 v[32:33], v[94:95], v[154:155], v[32:33]
	s_mov_b32 s44, 0x6588000
	v_lshl_add_u64 v[42:43], v[22:23], 0, s[44:45]
	global_store_dwordx2 v[42:43], v[94:95], off
	s_waitcnt vmcnt(45)
	v_pk_fma_f32 v[32:33], v[96:97], v[156:157], v[32:33]
	s_mov_b32 s44, 0x6589000
	v_lshl_add_u64 v[42:43], v[22:23], 0, s[44:45]
	global_store_dwordx2 v[42:43], v[96:97], off
	s_waitcnt vmcnt(45)
	v_pk_fma_f32 v[32:33], v[98:99], v[158:159], v[32:33]
	s_mov_b32 s44, 0x658a000
	v_lshl_add_u64 v[42:43], v[22:23], 0, s[44:45]
	global_store_dwordx2 v[42:43], v[98:99], off
	s_waitcnt vmcnt(43)
	v_pk_fma_f32 v[32:33], v[100:101], v[34:35], v[32:33]
	s_mov_b32 s44, 0x658b000
	v_lshl_add_u64 v[42:43], v[22:23], 0, s[44:45]
	global_store_dwordx2 v[42:43], v[100:101], off
	s_waitcnt vmcnt(43)
	v_pk_fma_f32 v[32:33], v[102:103], v[36:37], v[32:33]
	s_mov_b32 s44, 0x658c000
	v_lshl_add_u64 v[42:43], v[22:23], 0, s[44:45]
	global_store_dwordx2 v[42:43], v[102:103], off
	s_branch .LBB0_584

	.amdhsa_kernel _Z8mega_fwd6Params
		.amdhsa_group_segment_fixed_size 0
		.amdhsa_private_segment_fixed_size 0
		.amdhsa_kernarg_size 472
		.amdhsa_user_sgpr_count 2
		.amdhsa_user_sgpr_dispatch_ptr 0
		.amdhsa_user_sgpr_queue_ptr 0
		.amdhsa_user_sgpr_kernarg_segment_ptr 1
		.amdhsa_user_sgpr_dispatch_id 0
		.amdhsa_user_sgpr_kernarg_preload_length 0
		.amdhsa_user_sgpr_kernarg_preload_offset 0
		.amdhsa_user_sgpr_private_segment_size 0
		.amdhsa_uses_dynamic_stack 0
		.amdhsa_enable_private_segment 0
		.amdhsa_system_sgpr_workgroup_id_x 1
		.amdhsa_system_sgpr_workgroup_id_y 0
		.amdhsa_system_sgpr_workgroup_id_z 0
		.amdhsa_system_sgpr_workgroup_info 0
		.amdhsa_system_vgpr_workitem_id 2
		.amdhsa_next_free_vgpr 256
		.amdhsa_next_free_sgpr 102
		.amdhsa_accum_offset 256
		.amdhsa_reserve_vcc 1
		.amdhsa_float_round_mode_32 0
		.amdhsa_float_round_mode_16_64 0
		.amdhsa_float_denorm_mode_32 3
		.amdhsa_float_denorm_mode_16_64 3
		.amdhsa_dx10_clamp 1
		.amdhsa_ieee_mode 1
		.amdhsa_fp16_overflow 0
		.amdhsa_tg_split 0
		.amdhsa_exception_fp_ieee_invalid_op 0
		.amdhsa_exception_fp_denorm_src 0
		.amdhsa_exception_fp_ieee_div_zero 0
		.amdhsa_exception_fp_ieee_overflow 0
		.amdhsa_exception_fp_ieee_underflow 0
		.amdhsa_exception_fp_ieee_inexact 0
		.amdhsa_exception_int_div_zero 0
	.end_amdhsa_kernel

amdhsa.kernels:
  - .agpr_count:     0
    .args:
      - .offset:         0
        .size:           216
        .value_kind:     by_value
      - .offset:         216
        .size:           4
        .value_kind:     hidden_block_count_x
      - .offset:         220
        .size:           4
        .value_kind:     hidden_block_count_y
      - .offset:         224
        .size:           4
        .value_kind:     hidden_block_count_z
      - .offset:         228
        .size:           2
        .value_kind:     hidden_group_size_x
      - .offset:         230
        .size:           2
        .value_kind:     hidden_group_size_y
      - .offset:         232
        .size:           2
        .value_kind:     hidden_group_size_z
      - .offset:         234
        .size:           2
        .value_kind:     hidden_remainder_x
      - .offset:         236
        .size:           2
        .value_kind:     hidden_remainder_y
      - .offset:         238
        .size:           2
        .value_kind:     hidden_remainder_z
      - .offset:         256
        .size:           8
        .value_kind:     hidden_global_offset_x
      - .offset:         264
        .size:           8
        .value_kind:     hidden_global_offset_y
      - .offset:         272
        .size:           8
        .value_kind:     hidden_global_offset_z
      - .offset:         280
        .size:           2
        .value_kind:     hidden_grid_dims
      - .offset:         304
        .size:           8
        .value_kind:     hidden_multigrid_sync_arg
      - .offset:         336
        .size:           4
        .value_kind:     hidden_dynamic_lds_size
    .group_segment_fixed_size: 0
    .kernarg_segment_align: 8
    .kernarg_segment_size: 472
    .language:       OpenCL C
    .language_version:
      - 2
      - 0
    .max_flat_workgroup_size: 512
    .name:           _Z8mega_fwd6Params
    .private_segment_fixed_size: 0
    .sgpr_count:     108
    .sgpr_spill_count: 282
    .symbol:         _Z8mega_fwd6Params.kd
    .uniform_work_group_size: 1
    .uses_dynamic_stack: false
    .vgpr_count:     256
    .vgpr_spill_count: 0
    .wavefront_size: 64
